# ELEM2 panel order flipped to newest-first (h panels the FFN-in GEMM reads first are written last) on top of v001
# speedup vs baseline: 1.0128x; 1.0128x over previous
; template <int x_mode_in>
; __device__ __forceinline__ void phase_elem(const Params& p, bool prev, bool has_y, int l_res, int jg, int ngi_res, int x_mode_out, bool write_h, int l_h, int jsh, int ngi_h) {
;     ...
;         const int pos = prev ? 383 - (b >> 4) : (b >> 4), pmo = 48 * ((pos & 63) >> 3) + 8 * (pos >> 6) + (pos & 7);
;         const int tok0 = pmo * 256 + (b & 15) * 16, s = seq_of(tok0);
;         f32x4 ar[2][2], ah[2][2], sh[2][2];
; #pragma unroll
;         for (int j = 0; j < 2; ++j)
; #pragma unroll
;             for (int k = 0; k < 2; ++k) { ar[j][k] = (f32x4){0.f, 0.f, 0.f, 0.f}; ah[j][k] = ar[j][k]; sh[j][k] = ar[j][k]; }
;         if (has_y) { const float* gp = mod + (((size_t)s * 4 + l_res) * 6 + jg) * 1024 + 8 * lane; const float* np = norm_g + (l_res * 4 + ngi_res) * 1024 + 8 * lane;
; #pragma unroll
;             for (int j = 0; j < 2; ++j)
; #pragma unroll
;                 for (int k = 0; k < 2; ++k) ar[j][k] = *(const f32x4*)(gp + 512 * j + 4 * k) * *(const f32x4*)(np + 512 * j + 4 * k); }
;         if (write_h) { const float* shp = mod + (((size_t)s * 4 + l_h) * 6 + jsh) * 1024 + 8 * lane; const float* scp = shp + 1024; const float* np = norm_g + (l_h * 4 + ngi_h) * 1024 + 8 * lane;
; #pragma unroll
;             for (int j = 0; j < 2; ++j)
; #pragma unroll
;                 for (int k = 0; k < 2; ++k) { ah[j][k] = *(const f32x4*)(np + 512 * j + 4 * k) * (*(const f32x4*)(scp + 512 * j + 4 * k) + 1.0f); sh[j][k] = *(const f32x4*)(shp + 512 * j + 4 * k); } }
;         f32x4 xr[2][2][2][2]; u32x4 xb[2][2][2], yb[2][2][2];
;     ...
;         ELEM_LOAD(0, tok0);
.LBB0_505:
	s_ashr_i32 s0, s2, 4
	s_sub_i32 s0, 0x17f, s0
	s_bfe_u32 s1, s0, 0x30003
	s_lshr_b32 s4, s0, 3
	s_mul_i32 s1, s1, 48
	s_and_b32 s4, s4, -8
	s_add_i32 s1, s1, s4
	s_and_b32 s0, s0, 7
	s_or_b32 s0, s1, s0
	s_lshl_b32 s9, s0, 8
	s_lshl_b32 s0, s2, 4
	s_add_i32 s4, s9, 0xffff0000
	s_and_b32 s0, s0, 0xf0
	s_lshr_b32 s4, s4, 13
	s_and_b32 s8, s3, 0xf0
	s_or_b32 s0, s9, s0
	s_add_i32 s4, s4, 32
	s_ashr_i32 s1, s1, 3
	s_cmp_lt_i32 s0, 0x10000
	s_cselect_b32 s10, s1, s4
	s_ashr_i32 s11, s10, 31
	s_lshl_b64 s[10:11], s[10:11], 2
	v_readlane_b32 s4, v248, 63
	s_add_u32 s1, s10, s4
	s_addc_u32 s4, s11, 0
	s_mulk_i32 s4, 0x6000
	s_waitcnt vmcnt(15)
	v_mad_u64_u32 v[18:19], s[10:11], s1, v212, v[86:87]
	s_movk_i32 s1, 0x2000
	v_add_u32_e32 v19, s4, v19
	v_add_co_u32_e32 v20, vcc, s1, v18
	v_readlane_b32 s5, v246, 0
	s_nop 0
	v_addc_co_u32_e32 v21, vcc, 0, v19, vcc
	s_mov_b64 s[4:5], 0x2000
	s_waitcnt vmcnt(13)
	v_add_co_u32_e32 v26, vcc, s7, v18
	v_lshl_add_u64 v[6:7], v[18:19], 0, s[4:5]
	s_nop 0
	v_addc_co_u32_e32 v27, vcc, 0, v19, vcc
	global_load_dwordx4 v[2:5], v[26:27], off offset:-4096
	s_nop 0
	global_load_dwordx4 v[6:9], v[6:7], off offset:16
	s_nop 0
	global_load_dwordx4 v[10:13], v[88:89], off offset:16
	global_load_dwordx4 v[14:17], v[88:89], off
	s_mov_b64 s[10:11], 0x2800
	s_movk_i32 s1, 0x4000
	v_add_co_u32_e32 v22, vcc, s1, v18
	s_ashr_i32 s1, s0, 31
	s_nop 0
	v_addc_co_u32_e32 v23, vcc, 0, v19, vcc
	s_or_b32 s36, s9, s8
	s_ashr_i32 s37, s36, 31
	s_mov_b32 s4, 0
	s_mov_b32 s6, 0x3a800000
	s_waitcnt vmcnt(1)
	v_pk_mul_f32 v[102:103], v[6:7], v[10:11]
	v_lshl_add_u64 v[6:7], v[18:19], 0, s[10:11]
	s_waitcnt vmcnt(0)
	v_pk_mul_f32 v[96:97], v[4:5], v[16:17]
	v_pk_mul_f32 v[98:99], v[2:3], v[14:15]
	v_pk_mul_f32 v[100:101], v[8:9], v[12:13]
	global_load_dwordx4 v[2:5], v[20:21], off offset:2048
	s_nop 0
	global_load_dwordx4 v[6:9], v[6:7], off offset:16
	s_nop 0
	global_load_dwordx4 v[10:13], v[88:89], off offset:2064
	global_load_dwordx4 v[14:17], v[88:89], off offset:2048
	s_mov_b64 s[10:11], 0x3000
	v_lshl_add_u64 v[20:21], v[18:19], 0, s[10:11]
	s_mov_b64 s[10:11], 0x4000
	s_waitcnt vmcnt(1)
	v_pk_mul_f32 v[108:109], v[8:9], v[12:13]
	s_waitcnt vmcnt(0)
	v_pk_mul_f32 v[106:107], v[2:3], v[14:15]
	v_lshl_add_u64 v[14:15], v[18:19], 0, s[10:11]
	v_pk_mul_f32 v[104:105], v[4:5], v[16:17]
	v_pk_mul_f32 v[110:111], v[6:7], v[10:11]
	global_load_dwordx4 v[10:13], v[90:91], off offset:16
	global_load_dwordx4 v[2:5], v[90:91], off
	global_load_dwordx4 v[6:9], v[22:23], off
	s_nop 0
	global_load_dwordx4 v[14:17], v[14:15], off offset:16
	s_mov_b64 s[10:11], 0x4800
	v_lshl_add_u64 v[24:25], v[18:19], 0, s[10:11]
	s_mov_b64 s[10:11], 0x3800
	v_lshl_add_u64 v[28:29], v[18:19], 0, s[10:11]
	s_lshl_b64 s[10:11], s[0:1], 12
	s_waitcnt vmcnt(1)
	v_pk_add_f32 v[8:9], v[8:9], 1.0 op_sel_hi:[1,0]
	v_pk_add_f32 v[6:7], v[6:7], 1.0 op_sel_hi:[1,0]
	s_waitcnt vmcnt(0)
	v_pk_add_f32 v[16:17], v[16:17], 1.0 op_sel_hi:[1,0]
	v_pk_add_f32 v[14:15], v[14:15], 1.0 op_sel_hi:[1,0]
	v_pk_mul_f32 v[112:113], v[4:5], v[8:9]
	v_pk_mul_f32 v[114:115], v[2:3], v[6:7]
	global_load_dwordx4 v[2:5], v[26:27], off
	global_load_dwordx4 v[6:9], v[20:21], off offset:16
	v_pk_mul_f32 v[116:117], v[12:13], v[16:17]
	v_pk_mul_f32 v[118:119], v[10:11], v[14:15]
	global_load_dwordx4 v[18:21], v[90:91], off offset:2064
	global_load_dwordx4 v[10:13], v[90:91], off offset:2048
	global_load_dwordx4 v[14:17], v[22:23], off offset:2048
	s_nop 0
	global_load_dwordx4 v[22:25], v[24:25], off offset:16
	s_waitcnt vmcnt(1)
	v_pk_add_f32 v[16:17], v[16:17], 1.0 op_sel_hi:[1,0]
	s_waitcnt vmcnt(0)
	v_pk_add_f32 v[22:23], v[22:23], 1.0 op_sel_hi:[1,0]
	v_pk_add_f32 v[14:15], v[14:15], 1.0 op_sel_hi:[1,0]
	v_pk_mul_f32 v[126:127], v[18:19], v[22:23]
	v_lshl_add_u64 v[22:23], v[92:93], 0, s[10:11]
	s_lshl_b64 s[10:11], s[0:1], 11
	s_or_b32 s0, s0, 1
	s_ashr_i32 s1, s0, 31
	v_lshl_add_u64 v[30:31], v[94:95], 0, s[10:11]
	s_lshl_b64 s[10:11], s[0:1], 12
	s_lshl_b64 s[0:1], s[0:1], 11
	v_pk_add_f32 v[24:25], v[24:25], 1.0 op_sel_hi:[1,0]
	v_lshl_add_u64 v[38:39], v[92:93], 0, s[10:11]
	v_lshl_add_u64 v[46:47], v[94:95], 0, s[0:1]
	v_pk_mul_f32 v[120:121], v[12:13], v[16:17]
	v_pk_mul_f32 v[122:123], v[10:11], v[14:15]
	global_load_dwordx4 v[10:13], v[26:27], off offset:2048
	global_load_dwordx4 v[14:17], v[28:29], off offset:16
	v_pk_mul_f32 v[124:125], v[20:21], v[24:25]
	global_load_dwordx4 v[18:21], v[22:23], off
	s_nop 0
	global_load_dwordx4 v[22:25], v[22:23], off offset:1024
	s_nop 0
	global_load_dwordx4 v[26:29], v[30:31], off
	s_nop 0
	global_load_dwordx4 v[30:33], v[30:31], off offset:1024
	s_nop 0
	global_load_dwordx4 v[34:37], v[38:39], off
	s_nop 0
	global_load_dwordx4 v[38:41], v[38:39], off offset:1024
	s_nop 0
	global_load_dwordx4 v[42:45], v[46:47], off
	s_nop 0
	global_load_dwordx4 v[46:49], v[46:47], off offset:1024
	s_lshl_b64 s[0:1], s[36:37], 11
	s_add_u32 s38, s26, s0
	s_addc_u32 s39, s27, s1
	s_lshl_b64 s[0:1], s[36:37], 12
	s_add_u32 s8, s24, s0
	s_addc_u32 s9, s25, s1
	s_branch .LBB0_507

; template <int x_mode_in>
; __device__ __forceinline__ void phase_elem(const Params& p, bool prev, bool has_y, int l_res, int jg, int ngi_res, int x_mode_out, bool write_h, int l_h, int jsh, int ngi_h) {
;     ...
;         const int pos = prev ? 383 - (b >> 4) : (b >> 4), pmo = 48 * ((pos & 63) >> 3) + 8 * (pos >> 6) + (pos & 7);
;         const int tok0 = pmo * 256 + (b & 15) * 16, s = seq_of(tok0);
;         f32x4 ar[2][2], ah[2][2], sh[2][2];
; #pragma unroll
;         for (int j = 0; j < 2; ++j)
; #pragma unroll
;             for (int k = 0; k < 2; ++k) { ar[j][k] = (f32x4){0.f, 0.f, 0.f, 0.f}; ah[j][k] = ar[j][k]; sh[j][k] = ar[j][k]; }
;         if (has_y) { const float* gp = mod + (((size_t)s * 4 + l_res) * 6 + jg) * 1024 + 8 * lane; const float* np = norm_g + (l_res * 4 + ngi_res) * 1024 + 8 * lane;
; #pragma unroll
;             for (int j = 0; j < 2; ++j)
; #pragma unroll
;                 for (int k = 0; k < 2; ++k) ar[j][k] = *(const f32x4*)(gp + 512 * j + 4 * k) * *(const f32x4*)(np + 512 * j + 4 * k); }
;         if (write_h) { const float* shp = mod + (((size_t)s * 4 + l_h) * 6 + jsh) * 1024 + 8 * lane; const float* scp = shp + 1024; const float* np = norm_g + (l_h * 4 + ngi_h) * 1024 + 8 * lane;
; #pragma unroll
;             for (int j = 0; j < 2; ++j)
; #pragma unroll
;                 for (int k = 0; k < 2; ++k) { ah[j][k] = *(const f32x4*)(np + 512 * j + 4 * k) * (*(const f32x4*)(scp + 512 * j + 4 * k) + 1.0f); sh[j][k] = *(const f32x4*)(shp + 512 * j + 4 * k); } }
;         f32x4 xr[2][2][2][2]; u32x4 xb[2][2][2], yb[2][2][2];
;     ...
;         ELEM_LOAD(0, tok0);
.LBB0_514:
	s_ashr_i32 s0, s4, 4
	s_sub_i32 s0, 0x17f, s0
	s_bfe_u32 s1, s0, 0x30003
	s_lshr_b32 s2, s0, 3
	s_mul_i32 s1, s1, 48
	s_and_b32 s2, s2, -8
	s_add_i32 s1, s1, s2
	s_and_b32 s0, s0, 7
	s_or_b32 s0, s1, s0
	s_lshl_b32 s11, s0, 8
	s_lshl_b32 s0, s4, 4
	s_and_b32 s0, s0, 0xf0
	s_and_b32 s9, s8, 0xf0
	s_or_b32 s0, s11, s0
	s_cmp_lt_i32 s0, 0x10000
	s_cselect_b64 s[2:3], -1, 0
	s_add_i32 s10, s11, 0xffff0000
	s_lshr_b32 s5, s10, 13
	s_add_i32 s5, s5, 32
	s_lshr_b32 s1, s1, 3
	s_and_b64 s[34:35], s[2:3], exec
	s_cselect_b32 s1, s1, s5
	s_mul_i32 s1, s1, 24
	s_or_b32 s34, s1, 2
	s_ashr_i32 s35, s34, 31
	s_lshl_b64 s[34:35], s[34:35], 12
	s_waitcnt vmcnt(15)
	v_lshl_add_u64 v[18:19], v[114:115], 0, s[34:35]
	global_load_dwordx4 v[2:5], v[18:19], off offset:16
	global_load_dwordx4 v[6:9], v[18:19], off
	global_load_dwordx4 v[10:13], v[116:117], off offset:16
	global_load_dwordx4 v[14:17], v[116:117], off
	s_or_b32 s34, s1, 3
	s_ashr_i32 s35, s34, 31
	s_lshl_b64 s[34:35], s[34:35], 12
	s_waitcnt vmcnt(17)
	v_lshl_add_u64 v[26:27], v[114:115], 0, s[34:35]
	s_mov_b64 s[34:35], 0x1000
	v_add_co_u32_e32 v22, vcc, s83, v26
	v_readlane_b32 s44, v247, 33
	s_nop 0
	v_addc_co_u32_e32 v23, vcc, 0, v27, vcc
	s_add_i32 s5, s0, 0xffff0000
	s_ashr_i32 s1, s0, 31
	v_readlane_b32 s45, v247, 34
	s_and_b64 s[2:3], s[2:3], exec
	v_readlane_b32 s46, v247, 35
	v_readlane_b32 s47, v247, 36
	s_mov_b64 s[36:37], s[44:45]
	s_cselect_b32 s3, s1, 0
	s_cselect_b32 s2, s0, s5
	s_mov_b64 s[38:39], s[46:47]
	s_cselect_b32 s5, s37, s39
	s_cselect_b32 s33, s36, s38
	s_lshl_b64 s[2:3], s[2:3], 12
	s_add_u32 s2, s33, s2
	s_addc_u32 s3, s5, s3
	s_mov_b64 s[44:45], 0
	s_mov_b32 s6, 0x3a800000
	v_readlane_b32 s48, v247, 37
	v_readlane_b32 s49, v247, 38
	v_readlane_b32 s50, v247, 39
	v_readlane_b32 s51, v247, 40
	v_readlane_b32 s52, v247, 41
	v_readlane_b32 s53, v247, 42
	v_readlane_b32 s54, v247, 43
	v_readlane_b32 s55, v247, 44
	v_readlane_b32 s56, v247, 45
	v_readlane_b32 s57, v247, 46
	v_readlane_b32 s58, v247, 47
	v_readlane_b32 s59, v247, 48
	s_waitcnt vmcnt(1)
	v_pk_mul_f32 v[126:127], v[4:5], v[12:13]
	s_waitcnt vmcnt(0)
	v_pk_mul_f32 v[122:123], v[8:9], v[16:17]
	v_pk_mul_f32 v[124:125], v[6:7], v[14:15]
	v_pk_mul_f32 v[128:129], v[2:3], v[10:11]
	global_load_dwordx4 v[2:5], v[18:19], off offset:2064
	global_load_dwordx4 v[6:9], v[18:19], off offset:2048
	global_load_dwordx4 v[10:13], v[116:117], off offset:2064
	global_load_dwordx4 v[14:17], v[116:117], off offset:2048
	s_waitcnt vmcnt(1)
	v_pk_mul_f32 v[134:135], v[4:5], v[12:13]
	s_waitcnt vmcnt(0)
	v_pk_mul_f32 v[132:133], v[6:7], v[14:15]
	v_lshl_add_u64 v[14:15], v[26:27], 0, s[34:35]
	v_pk_mul_f32 v[130:131], v[8:9], v[16:17]
	v_pk_mul_f32 v[136:137], v[2:3], v[10:11]
	global_load_dwordx4 v[10:13], v[118:119], off offset:16
	global_load_dwordx4 v[2:5], v[118:119], off
	global_load_dwordx4 v[6:9], v[22:23], off
	s_nop 0
	global_load_dwordx4 v[14:17], v[14:15], off offset:16
	s_mov_b64 s[34:35], 0x1800
	v_lshl_add_u64 v[24:25], v[26:27], 0, s[34:35]
	s_waitcnt vmcnt(1)
	v_pk_add_f32 v[8:9], v[8:9], 1.0 op_sel_hi:[1,0]
	v_pk_add_f32 v[6:7], v[6:7], 1.0 op_sel_hi:[1,0]
	s_waitcnt vmcnt(0)
	v_pk_add_f32 v[16:17], v[16:17], 1.0 op_sel_hi:[1,0]
	v_pk_add_f32 v[14:15], v[14:15], 1.0 op_sel_hi:[1,0]
	v_pk_mul_f32 v[138:139], v[4:5], v[8:9]
	v_pk_mul_f32 v[140:141], v[2:3], v[6:7]
	global_load_dwordx4 v[2:5], v[26:27], off offset:16
	global_load_dwordx4 v[6:9], v[26:27], off
	v_pk_mul_f32 v[142:143], v[12:13], v[16:17]
	v_pk_mul_f32 v[144:145], v[10:11], v[14:15]
	global_load_dwordx4 v[18:21], v[118:119], off offset:2064
	global_load_dwordx4 v[10:13], v[118:119], off offset:2048
	global_load_dwordx4 v[14:17], v[22:23], off offset:2048
	s_nop 0
	global_load_dwordx4 v[22:25], v[24:25], off offset:16
	s_waitcnt vmcnt(1)
	v_pk_add_f32 v[16:17], v[16:17], 1.0 op_sel_hi:[1,0]
	v_pk_add_f32 v[14:15], v[14:15], 1.0 op_sel_hi:[1,0]
	s_waitcnt vmcnt(0)
	v_pk_add_f32 v[24:25], v[24:25], 1.0 op_sel_hi:[1,0]
	v_pk_add_f32 v[22:23], v[22:23], 1.0 op_sel_hi:[1,0]
	v_pk_mul_f32 v[156:157], v[12:13], v[16:17]
	v_pk_mul_f32 v[158:159], v[10:11], v[14:15]
	global_load_dwordx4 v[10:13], v[26:27], off offset:2064
	global_load_dwordx4 v[14:17], v[26:27], off offset:2048
	v_pk_mul_f32 v[160:161], v[20:21], v[24:25]
	v_pk_mul_f32 v[162:163], v[18:19], v[22:23]
	global_load_dwordx4 v[18:21], v220, s[2:3] offset:16
	global_load_dwordx4 v[22:25], v220, s[2:3]
	global_load_dwordx4 v[26:29], v220, s[2:3] offset:2064
	global_load_dwordx4 v[30:33], v220, s[2:3] offset:2048
	s_lshl_b64 s[2:3], s[0:1], 11
	v_lshl_add_u64 v[38:39], v[120:121], 0, s[2:3]
	s_or_b32 s2, s0, 1
	s_ashr_i32 s3, s2, 31
	s_add_i32 s0, s0, 0xffff0001
	s_cmp_lt_i32 s2, 0x10000
	s_cselect_b32 s1, s3, 0
	s_cselect_b32 s0, s2, s0
	s_cselect_b32 s5, s37, s39
	s_cselect_b32 s33, s36, s38
	s_lshl_b64 s[0:1], s[0:1], 12
	s_add_u32 s0, s33, s0
	s_addc_u32 s1, s5, s1
	global_load_dwordx4 v[34:37], v[38:39], off
	s_nop 0
	global_load_dwordx4 v[38:41], v[38:39], off offset:1024
	s_nop 0
	global_load_dwordx4 v[42:45], v220, s[0:1] offset:16
	global_load_dwordx4 v[46:49], v220, s[0:1]
	global_load_dwordx4 v[50:53], v220, s[0:1] offset:2064
	global_load_dwordx4 v[54:57], v220, s[0:1] offset:2048
	s_lshl_b64 s[0:1], s[2:3], 11
	v_lshl_add_u64 v[62:63], v[120:121], 0, s[0:1]
	global_load_dwordx4 v[58:61], v[62:63], off
	s_nop 0
	global_load_dwordx4 v[62:65], v[62:63], off offset:1024
	s_or_b32 s36, s11, s9
	s_ashr_i32 s37, s36, 31
	s_lshl_b64 s[0:1], s[36:37], 11
	s_add_u32 s38, s26, s0
	s_addc_u32 s39, s27, s1
	s_lshl_b64 s[0:1], s[36:37], 12
	s_add_u32 s40, s24, s0
	s_addc_u32 s41, s25, s1
	s_or_b32 s2, s10, s9
	s_branch .LBB0_516
